# adaLN GEMV (phase 0): 16 serialized weight loads per trip hoisted into one batched issue + single wait
# speedup vs baseline: 1.0185x; 1.0138x over previous
; __global__ void __launch_bounds__(512, 2) mk_fwd(Args args) {
;     ...
;                 const int hi = lane >> 5, cc = lane & 31;
;                 const float* wp = args.in[IN_WADA] + ((size_t)(l * 1024 + d0 + hi)) * 6144 + col0 + cc;
; #pragma unroll 16
;                 for (int i = 0; i < 64; ++i) { const float w = wp[(size_t)(2 * i) * 6144];
; #pragma unroll
;                     for (int b = 0; b < 17; ++b) acc[b] += sc[b * 128 + 2 * i + hi] * w; }
.LBB0_516:
	s_mul_i32 s46, s7, 0x3000
	v_lshl_add_u64 v[152:153], s[46:47], 2, v[74:75]
	global_load_dword v184, v[152:153], off
	s_mov_b32 s4, 0xc000
	v_add_co_u32_e32 v154, vcc, s4, v152
	s_mov_b32 s4, 0x18000
	s_nop 1
	v_addc_co_u32_e32 v155, vcc, 0, v153, vcc
	v_add_co_u32_e32 v156, vcc, s4, v152
	s_nop 1
	v_addc_co_u32_e32 v157, vcc, 0, v153, vcc
	s_mov_b32 s4, 0x24000
	s_mov_b32 s5, s47
	global_load_dword v185, v[154:155], off
	v_add_co_u32_e32 v158, vcc, s4, v152
	s_mov_b32 s4, 0x30000
	global_load_dword v186, v[156:157], off
	s_nop 1
	v_addc_co_u32_e32 v159, vcc, 0, v153, vcc
	global_load_dword v187, v[158:159], off
	v_add_co_u32_e32 v160, vcc, s4, v152
	s_nop 1
	v_addc_co_u32_e32 v161, vcc, 0, v153, vcc
	global_load_dword v188, v[160:161], off
	s_add_i32 s4, s46, 0xf000
	v_lshl_add_u64 v[162:163], s[4:5], 2, v[74:75]
	s_add_i32 s4, s46, 0x12000
	v_lshl_add_u64 v[166:167], s[4:5], 2, v[74:75]
	s_add_i32 s4, s46, 0x15000
	global_load_dword v189, v[162:163], off
	global_load_dword v190, v[166:167], off
	v_lshl_add_u64 v[168:169], s[4:5], 2, v[74:75]
	s_add_i32 s4, s46, 0x18000
	global_load_dword v191, v[168:169], off
	v_lshl_add_u64 v[170:171], s[4:5], 2, v[74:75]
	global_load_dword v192, v[170:171], off
	s_add_i32 s4, s46, 0x1b000
	v_lshl_add_u64 v[172:173], s[4:5], 2, v[74:75]
	global_load_dword v193, v[172:173], off
	s_add_i32 s4, s46, 0x1e000
	v_lshl_add_u64 v[170:171], s[4:5], 2, v[74:75]
	s_add_i32 s4, s46, 0x21000
	v_lshl_add_u64 v[168:169], s[4:5], 2, v[74:75]
	s_add_i32 s4, s46, 0x24000
	global_load_dword v194, v[170:171], off
	v_lshl_add_u64 v[170:171], s[4:5], 2, v[74:75]
	s_add_i32 s4, s46, 0x27000
	global_load_dword v195, v[168:169], off
	global_load_dword v196, v[170:171], off
	v_lshl_add_u64 v[174:175], s[4:5], 2, v[74:75]
	global_load_dword v197, v[174:175], off
	s_add_i32 s4, s46, 0x2a000
	v_lshl_add_u64 v[170:171], s[4:5], 2, v[74:75]
	s_add_i32 s46, s46, 0x2d000
	global_load_dword v198, v[170:171], off
	v_lshl_add_u64 v[168:169], s[46:47], 2, v[74:75]
	global_load_dword v199, v[168:169], off
	s_waitcnt vmcnt(0)
	s_mul_i32 s46, s7, 0x3000
	v_lshl_add_u64 v[82:83], s[46:47], 2, v[74:75]
	v_mov_b32_e32 v0, v184
	v_lshl_add_u32 v142, s7, 3, v129
	v_add_u32_e32 v141, 0x400, v142
	ds_read2_b32 v[86:87], v142 offset1:2
	ds_read2_b32 v[88:89], v142 offset0:4 offset1:6
	ds_read2_b32 v[78:79], v142 offset0:8 offset1:10
	ds_read2_b32 v[76:77], v142 offset0:12 offset1:14
	ds_read2_b32 v[92:93], v142 offset0:128 offset1:130
	ds_read2_b32 v[100:101], v141 offset1:2
	ds_read2_b32 v[102:103], v141 offset0:128 offset1:130
	v_add_u32_e32 v140, 0x800, v142
	v_add_u32_e32 v139, 0xc00, v142
	v_add_u32_e32 v138, 0x1000, v142
	s_waitcnt lgkmcnt(0)
	v_mov_b32_e32 v108, v100
	v_mov_b32_e32 v109, v102
	v_mov_b32_e32 v94, v86
	v_mov_b32_e32 v95, v92
	v_add_u32_e32 v134, 0x1400, v142
	v_add_u32_e32 v135, 0x1800, v142
	s_mov_b32 s4, 0xc000
	v_add_co_u32_e32 v150, vcc, s4, v82
	s_mov_b32 s4, 0x18000
	s_nop 0
	v_addc_co_u32_e32 v151, vcc, 0, v83, vcc
	v_add_co_u32_e32 v100, vcc, s4, v82
	v_mov_b32_e32 v92, v87
	v_mov_b32_e32 v102, v101
	v_addc_co_u32_e32 v101, vcc, 0, v83, vcc
	s_mov_b32 s4, 0x24000
	s_mov_b32 s5, s47
	s_add_i32 s7, s7, 16
	v_pk_fma_f32 v[106:107], v[0:1], v[108:109], v[106:107] op_sel_hi:[0,1,1]
	ds_read2_b32 v[108:109], v140 offset1:2
	ds_read2_b32 v[110:111], v140 offset0:128 offset1:130
	v_pk_fma_f32 v[94:95], v[0:1], v[94:95], v[120:121] op_sel_hi:[0,1,1]
	s_waitcnt lgkmcnt(1)
	v_mov_b32_e32 v112, v108
	s_waitcnt lgkmcnt(0)
	v_mov_b32_e32 v113, v110
	v_pk_fma_f32 v[104:105], v[0:1], v[112:113], v[104:105] op_sel_hi:[0,1,1]
	ds_read2_b32 v[112:113], v139 offset1:2
	ds_read2_b32 v[114:115], v139 offset0:128 offset1:130
	v_mov_b32_e32 v110, v109
	s_waitcnt lgkmcnt(1)
	v_mov_b32_e32 v116, v112
	s_waitcnt lgkmcnt(0)
	v_mov_b32_e32 v117, v114
	v_pk_fma_f32 v[98:99], v[0:1], v[116:117], v[98:99] op_sel_hi:[0,1,1]
	ds_read2_b32 v[116:117], v138 offset1:2
	ds_read2_b32 v[118:119], v138 offset0:128 offset1:130
	v_mov_b32_e32 v114, v113
	s_waitcnt lgkmcnt(1)
	v_mov_b32_e32 v120, v116
	s_waitcnt lgkmcnt(0)
	v_mov_b32_e32 v121, v118
	v_pk_fma_f32 v[96:97], v[0:1], v[120:121], v[96:97] op_sel_hi:[0,1,1]
	ds_read2_b32 v[120:121], v134 offset1:2
	ds_read2_b32 v[122:123], v134 offset0:128 offset1:130
	v_mov_b32_e32 v118, v117
	s_waitcnt lgkmcnt(1)
	v_mov_b32_e32 v124, v120
	s_waitcnt lgkmcnt(0)
	v_mov_b32_e32 v125, v122
	v_pk_fma_f32 v[90:91], v[0:1], v[124:125], v[90:91] op_sel_hi:[0,1,1]
	ds_read2_b32 v[124:125], v135 offset1:2
	ds_read2_b32 v[126:127], v135 offset0:128 offset1:130
	v_mov_b32_e32 v122, v121
	s_waitcnt lgkmcnt(1)
	v_mov_b32_e32 v136, v124
	s_waitcnt lgkmcnt(0)
	v_mov_b32_e32 v137, v126
	v_pk_fma_f32 v[84:85], v[0:1], v[136:137], v[84:85] op_sel_hi:[0,1,1]
	v_add_u32_e32 v136, 0x1c00, v142
	ds_read2_b32 v[144:145], v136 offset1:2
	ds_read2_b32 v[146:147], v136 offset0:128 offset1:130
	v_add_u32_e32 v137, 0x2000, v142
	v_mov_b32_e32 v126, v125
	s_waitcnt lgkmcnt(1)
	v_mov_b32_e32 v148, v144
	s_waitcnt lgkmcnt(0)
	v_mov_b32_e32 v149, v146
	v_pk_fma_f32 v[80:81], v[0:1], v[148:149], v[80:81] op_sel_hi:[0,1,1]
	ds_read2_b32 v[148:149], v137 offset1:2
	v_mov_b32_e32 v146, v145
	s_waitcnt lgkmcnt(0)
; __global__ void __launch_bounds__(512, 2) mk_fwd(Args args) {
;     ...
; #pragma unroll 16
;                 for (int i = 0; i < 64; ++i) { const float w = wp[(size_t)(2 * i) * 6144];
; #pragma unroll
;                     for (int b = 0; b < 17; ++b) acc[b] += sc[b * 128 + 2 * i + hi] * w; }
	v_fmac_f32_e32 v133, v0, v148
	v_mov_b32_e32 v0, v185
	v_add_co_u32_e32 v148, vcc, s4, v82
	s_mov_b32 s4, 0x30000
	v_pk_fma_f32 v[86:87], v[0:1], v[92:93], v[94:95] op_sel_hi:[0,1,1]
	v_pk_fma_f32 v[92:93], v[0:1], v[102:103], v[106:107] op_sel_hi:[0,1,1]
	v_pk_fma_f32 v[94:95], v[0:1], v[110:111], v[104:105] op_sel_hi:[0,1,1]
	v_pk_fma_f32 v[98:99], v[0:1], v[114:115], v[98:99] op_sel_hi:[0,1,1]
	v_pk_fma_f32 v[96:97], v[0:1], v[118:119], v[96:97] op_sel_hi:[0,1,1]
	v_pk_fma_f32 v[90:91], v[0:1], v[122:123], v[90:91] op_sel_hi:[0,1,1]
	v_pk_fma_f32 v[84:85], v[0:1], v[126:127], v[84:85] op_sel_hi:[0,1,1]
	v_pk_fma_f32 v[80:81], v[0:1], v[146:147], v[80:81] op_sel_hi:[0,1,1]
	v_fmac_f32_e32 v133, v0, v149
	v_mov_b32_e32 v0, v186
	ds_read2_b32 v[100:101], v142 offset0:132 offset1:134
	v_mov_b32_e32 v102, v88
	v_addc_co_u32_e32 v149, vcc, 0, v83, vcc
	s_waitcnt lgkmcnt(0)
	v_mov_b32_e32 v103, v100
	v_mov_b32_e32 v100, v89
	v_pk_fma_f32 v[86:87], v[0:1], v[102:103], v[86:87] op_sel_hi:[0,1,1]
	ds_read2_b32 v[102:103], v141 offset0:4 offset1:6
	ds_read2_b32 v[104:105], v141 offset0:132 offset1:134
	s_waitcnt lgkmcnt(1)
	v_mov_b32_e32 v106, v102
	s_waitcnt lgkmcnt(0)
	v_mov_b32_e32 v107, v104
	v_pk_fma_f32 v[92:93], v[0:1], v[106:107], v[92:93] op_sel_hi:[0,1,1]
	ds_read2_b32 v[106:107], v140 offset0:4 offset1:6
	ds_read2_b32 v[108:109], v140 offset0:132 offset1:134
	v_mov_b32_e32 v104, v103
	s_waitcnt lgkmcnt(1)
	v_mov_b32_e32 v110, v106
	s_waitcnt lgkmcnt(0)
	v_mov_b32_e32 v111, v108
	v_pk_fma_f32 v[94:95], v[0:1], v[110:111], v[94:95] op_sel_hi:[0,1,1]
	ds_read2_b32 v[110:111], v139 offset0:4 offset1:6
	ds_read2_b32 v[112:113], v139 offset0:132 offset1:134
	v_mov_b32_e32 v108, v107
	s_waitcnt lgkmcnt(1)
	v_mov_b32_e32 v114, v110
	s_waitcnt lgkmcnt(0)
	v_mov_b32_e32 v115, v112
	v_pk_fma_f32 v[98:99], v[0:1], v[114:115], v[98:99] op_sel_hi:[0,1,1]
	ds_read2_b32 v[114:115], v138 offset0:4 offset1:6
	ds_read2_b32 v[116:117], v138 offset0:132 offset1:134
	v_mov_b32_e32 v112, v111
	s_waitcnt lgkmcnt(1)
	v_mov_b32_e32 v118, v114
	s_waitcnt lgkmcnt(0)
	v_mov_b32_e32 v119, v116
	v_pk_fma_f32 v[96:97], v[0:1], v[118:119], v[96:97] op_sel_hi:[0,1,1]
	ds_read2_b32 v[118:119], v134 offset0:4 offset1:6
	ds_read2_b32 v[120:121], v134 offset0:132 offset1:134
	v_mov_b32_e32 v116, v115
	s_waitcnt lgkmcnt(1)
	v_mov_b32_e32 v122, v118
	s_waitcnt lgkmcnt(0)
	v_mov_b32_e32 v123, v120
	v_pk_fma_f32 v[90:91], v[0:1], v[122:123], v[90:91] op_sel_hi:[0,1,1]
	ds_read2_b32 v[122:123], v135 offset0:4 offset1:6
	ds_read2_b32 v[124:125], v135 offset0:132 offset1:134
	v_mov_b32_e32 v120, v119
	s_waitcnt lgkmcnt(1)
	v_mov_b32_e32 v126, v122
	s_waitcnt lgkmcnt(0)
	v_mov_b32_e32 v127, v124
	v_pk_fma_f32 v[84:85], v[0:1], v[126:127], v[84:85] op_sel_hi:[0,1,1]
	ds_read2_b32 v[126:127], v136 offset0:4 offset1:6
	ds_read2_b32 v[144:145], v136 offset0:132 offset1:134
	v_mov_b32_e32 v124, v123
	s_waitcnt lgkmcnt(1)
	v_mov_b32_e32 v146, v126
	s_waitcnt lgkmcnt(0)
	v_mov_b32_e32 v147, v144
	v_pk_fma_f32 v[80:81], v[0:1], v[146:147], v[80:81] op_sel_hi:[0,1,1]
	ds_read2_b32 v[146:147], v137 offset0:4 offset1:6
	v_mov_b32_e32 v144, v127
	s_waitcnt lgkmcnt(0)
	v_fmac_f32_e32 v133, v0, v146
	v_mov_b32_e32 v0, v187
	v_pk_fma_f32 v[118:119], v[0:1], v[124:125], v[84:85] op_sel_hi:[0,1,1]
	v_pk_fma_f32 v[124:125], v[0:1], v[144:145], v[80:81] op_sel_hi:[0,1,1]
	v_add_co_u32_e32 v80, vcc, s4, v82
	v_pk_fma_f32 v[86:87], v[0:1], v[100:101], v[86:87] op_sel_hi:[0,1,1]
	s_nop 0
	v_addc_co_u32_e32 v81, vcc, 0, v83, vcc
	v_pk_fma_f32 v[88:89], v[0:1], v[104:105], v[92:93] op_sel_hi:[0,1,1]
	v_pk_fma_f32 v[94:95], v[0:1], v[108:109], v[94:95] op_sel_hi:[0,1,1]
	v_pk_fma_f32 v[100:101], v[0:1], v[112:113], v[98:99] op_sel_hi:[0,1,1]
	v_pk_fma_f32 v[106:107], v[0:1], v[116:117], v[96:97] op_sel_hi:[0,1,1]
	v_pk_fma_f32 v[112:113], v[0:1], v[120:121], v[90:91] op_sel_hi:[0,1,1]
	v_fmac_f32_e32 v133, v0, v147
	v_mov_b32_e32 v0, v188
	ds_read2_b32 v[80:81], v142 offset0:136 offset1:138
	v_mov_b32_e32 v82, v78
	s_add_i32 s4, s46, 0xf000
	v_lshl_add_u64 v[144:145], s[4:5], 2, v[74:75]
	s_add_i32 s4, s46, 0x12000
	s_waitcnt lgkmcnt(0)
	v_mov_b32_e32 v83, v80
	v_mov_b32_e32 v80, v79
	v_lshl_add_u64 v[78:79], s[4:5], 2, v[74:75]
	s_add_i32 s4, s46, 0x15000
	v_pk_fma_f32 v[82:83], v[0:1], v[82:83], v[86:87] op_sel_hi:[0,1,1]
	ds_read2_b32 v[86:87], v141 offset0:8 offset1:10
	ds_read2_b32 v[84:85], v141 offset0:136 offset1:138
	s_waitcnt lgkmcnt(1)
	v_mov_b32_e32 v90, v86
	s_waitcnt lgkmcnt(0)
	v_mov_b32_e32 v91, v84
	v_pk_fma_f32 v[88:89], v[0:1], v[90:91], v[88:89] op_sel_hi:[0,1,1]
	ds_read2_b32 v[92:93], v140 offset0:8 offset1:10
	ds_read2_b32 v[90:91], v140 offset0:136 offset1:138
	v_mov_b32_e32 v84, v87
	s_waitcnt lgkmcnt(1)
	v_mov_b32_e32 v96, v92
	s_waitcnt lgkmcnt(0)
	v_mov_b32_e32 v97, v90
	v_pk_fma_f32 v[94:95], v[0:1], v[96:97], v[94:95] op_sel_hi:[0,1,1]
	ds_read2_b32 v[98:99], v139 offset0:8 offset1:10
	ds_read2_b32 v[96:97], v139 offset0:136 offset1:138
	v_mov_b32_e32 v90, v93
	s_waitcnt lgkmcnt(1)
	v_mov_b32_e32 v102, v98
	s_waitcnt lgkmcnt(0)
	v_mov_b32_e32 v103, v96
	v_pk_fma_f32 v[100:101], v[0:1], v[102:103], v[100:101] op_sel_hi:[0,1,1]
	ds_read2_b32 v[104:105], v138 offset0:8 offset1:10
	ds_read2_b32 v[102:103], v138 offset0:136 offset1:138
	v_mov_b32_e32 v96, v99
	s_waitcnt lgkmcnt(1)
	v_mov_b32_e32 v108, v104
	s_waitcnt lgkmcnt(0)
	v_mov_b32_e32 v109, v102
	v_pk_fma_f32 v[106:107], v[0:1], v[108:109], v[106:107] op_sel_hi:[0,1,1]
	ds_read2_b32 v[110:111], v134 offset0:8 offset1:10
	ds_read2_b32 v[108:109], v134 offset0:136 offset1:138
	v_mov_b32_e32 v102, v105
	s_waitcnt lgkmcnt(1)
; __global__ void __launch_bounds__(512, 2) mk_fwd(Args args) {
;     ...
; #pragma unroll 16
;                 for (int i = 0; i < 64; ++i) { const float w = wp[(size_t)(2 * i) * 6144];
; #pragma unroll
;                     for (int b = 0; b < 17; ++b) acc[b] += sc[b * 128 + 2 * i + hi] * w; }
	v_mov_b32_e32 v114, v110
	s_waitcnt lgkmcnt(0)
	v_mov_b32_e32 v115, v108
	v_pk_fma_f32 v[112:113], v[0:1], v[114:115], v[112:113] op_sel_hi:[0,1,1]
	ds_read2_b32 v[116:117], v135 offset0:8 offset1:10
	ds_read2_b32 v[114:115], v135 offset0:136 offset1:138
	v_mov_b32_e32 v108, v111
	s_waitcnt lgkmcnt(1)
	v_mov_b32_e32 v120, v116
	s_waitcnt lgkmcnt(0)
	v_mov_b32_e32 v121, v114
	v_pk_fma_f32 v[118:119], v[0:1], v[120:121], v[118:119] op_sel_hi:[0,1,1]
	ds_read2_b32 v[122:123], v136 offset0:8 offset1:10
	ds_read2_b32 v[120:121], v136 offset0:136 offset1:138
	v_mov_b32_e32 v114, v117
	s_waitcnt lgkmcnt(1)
	v_mov_b32_e32 v126, v122
	s_waitcnt lgkmcnt(0)
	v_mov_b32_e32 v127, v120
	v_pk_fma_f32 v[124:125], v[0:1], v[126:127], v[124:125] op_sel_hi:[0,1,1]
	ds_read2_b32 v[126:127], v137 offset0:8 offset1:10
	v_mov_b32_e32 v120, v123
	s_waitcnt lgkmcnt(0)
	v_fmac_f32_e32 v133, v0, v126
	v_mov_b32_e32 v0, v189
	v_pk_fma_f32 v[80:81], v[0:1], v[80:81], v[82:83] op_sel_hi:[0,1,1]
	v_pk_fma_f32 v[82:83], v[0:1], v[84:85], v[88:89] op_sel_hi:[0,1,1]
	v_pk_fma_f32 v[84:85], v[0:1], v[90:91], v[94:95] op_sel_hi:[0,1,1]
	v_pk_fma_f32 v[86:87], v[0:1], v[96:97], v[100:101] op_sel_hi:[0,1,1]
	v_pk_fma_f32 v[88:89], v[0:1], v[102:103], v[106:107] op_sel_hi:[0,1,1]
	v_pk_fma_f32 v[90:91], v[0:1], v[108:109], v[112:113] op_sel_hi:[0,1,1]
	v_pk_fma_f32 v[92:93], v[0:1], v[114:115], v[118:119] op_sel_hi:[0,1,1]
	v_pk_fma_f32 v[94:95], v[0:1], v[120:121], v[124:125] op_sel_hi:[0,1,1]
	v_fmac_f32_e32 v133, v0, v127
	v_mov_b32_e32 v0, v190
	ds_read2_b32 v[78:79], v142 offset0:140 offset1:142
	v_mov_b32_e32 v96, v76
	v_lshl_add_u64 v[126:127], s[4:5], 2, v[74:75]
	s_add_i32 s4, s46, 0x18000
	s_waitcnt lgkmcnt(0)
	v_mov_b32_e32 v97, v78
	v_mov_b32_e32 v78, v77
	v_pk_fma_f32 v[80:81], v[0:1], v[96:97], v[80:81] op_sel_hi:[0,1,1]
	ds_read2_b32 v[96:97], v141 offset0:12 offset1:14
	ds_read2_b32 v[98:99], v141 offset0:140 offset1:142
	s_waitcnt lgkmcnt(1)
	v_mov_b32_e32 v100, v96
	s_waitcnt lgkmcnt(0)
	v_mov_b32_e32 v101, v98
	v_pk_fma_f32 v[82:83], v[0:1], v[100:101], v[82:83] op_sel_hi:[0,1,1]
	ds_read2_b32 v[100:101], v140 offset0:12 offset1:14
	ds_read2_b32 v[102:103], v140 offset0:140 offset1:142
	v_mov_b32_e32 v98, v97
	s_waitcnt lgkmcnt(1)
	v_mov_b32_e32 v104, v100
	s_waitcnt lgkmcnt(0)
	v_mov_b32_e32 v105, v102
	v_pk_fma_f32 v[84:85], v[0:1], v[104:105], v[84:85] op_sel_hi:[0,1,1]
	ds_read2_b32 v[104:105], v139 offset0:12 offset1:14
	ds_read2_b32 v[106:107], v139 offset0:140 offset1:142
	v_mov_b32_e32 v102, v101
	s_waitcnt lgkmcnt(1)
	v_mov_b32_e32 v108, v104
	s_waitcnt lgkmcnt(0)
	v_mov_b32_e32 v109, v106
	v_pk_fma_f32 v[86:87], v[0:1], v[108:109], v[86:87] op_sel_hi:[0,1,1]
	ds_read2_b32 v[108:109], v138 offset0:12 offset1:14
	ds_read2_b32 v[110:111], v138 offset0:140 offset1:142
	v_mov_b32_e32 v106, v105
	s_waitcnt lgkmcnt(1)
	v_mov_b32_e32 v112, v108
	s_waitcnt lgkmcnt(0)
	v_mov_b32_e32 v113, v110
	v_pk_fma_f32 v[88:89], v[0:1], v[112:113], v[88:89] op_sel_hi:[0,1,1]
	ds_read2_b32 v[112:113], v134 offset0:12 offset1:14
	ds_read2_b32 v[114:115], v134 offset0:140 offset1:142
	v_mov_b32_e32 v110, v109
	s_waitcnt lgkmcnt(1)
	v_mov_b32_e32 v116, v112
	s_waitcnt lgkmcnt(0)
	v_mov_b32_e32 v117, v114
	v_pk_fma_f32 v[90:91], v[0:1], v[116:117], v[90:91] op_sel_hi:[0,1,1]
	ds_read2_b32 v[116:117], v135 offset0:12 offset1:14
	ds_read2_b32 v[118:119], v135 offset0:140 offset1:142
	v_mov_b32_e32 v114, v113
	s_waitcnt lgkmcnt(1)
	v_mov_b32_e32 v120, v116
	s_waitcnt lgkmcnt(0)
	v_mov_b32_e32 v121, v118
	v_pk_fma_f32 v[92:93], v[0:1], v[120:121], v[92:93] op_sel_hi:[0,1,1]
	ds_read2_b32 v[120:121], v136 offset0:12 offset1:14
	ds_read2_b32 v[122:123], v136 offset0:140 offset1:142
	v_mov_b32_e32 v118, v117
	s_waitcnt lgkmcnt(1)
	v_mov_b32_e32 v124, v120
	s_waitcnt lgkmcnt(0)
	v_mov_b32_e32 v125, v122
	v_pk_fma_f32 v[94:95], v[0:1], v[124:125], v[94:95] op_sel_hi:[0,1,1]
	ds_read2_b32 v[124:125], v137 offset0:12 offset1:14
	v_mov_b32_e32 v122, v121
	s_waitcnt lgkmcnt(0)
	v_fmac_f32_e32 v133, v0, v124
	v_mov_b32_e32 v0, v191
	v_pk_fma_f32 v[76:77], v[0:1], v[78:79], v[80:81] op_sel_hi:[0,1,1]
	v_pk_fma_f32 v[80:81], v[0:1], v[102:103], v[84:85] op_sel_hi:[0,1,1]
	v_pk_fma_f32 v[84:85], v[0:1], v[110:111], v[88:89] op_sel_hi:[0,1,1]
	v_pk_fma_f32 v[88:89], v[0:1], v[118:119], v[92:93] op_sel_hi:[0,1,1]
	v_lshl_add_u64 v[92:93], s[4:5], 2, v[74:75]
	v_pk_fma_f32 v[78:79], v[0:1], v[98:99], v[82:83] op_sel_hi:[0,1,1]
	v_pk_fma_f32 v[82:83], v[0:1], v[106:107], v[86:87] op_sel_hi:[0,1,1]
	v_pk_fma_f32 v[86:87], v[0:1], v[114:115], v[90:91] op_sel_hi:[0,1,1]
	v_pk_fma_f32 v[90:91], v[0:1], v[122:123], v[94:95] op_sel_hi:[0,1,1]
	v_fmac_f32_e32 v133, v0, v125
	v_mov_b32_e32 v0, v192
	ds_read2_b32 v[92:93], v142 offset0:16 offset1:18
	ds_read2_b32 v[94:95], v142 offset0:144 offset1:146
	s_add_i32 s4, s46, 0x1b000
	s_waitcnt lgkmcnt(1)
	v_mov_b32_e32 v96, v92
	s_waitcnt lgkmcnt(0)
	v_mov_b32_e32 v97, v94
	v_mov_b32_e32 v94, v93
	v_pk_fma_f32 v[76:77], v[0:1], v[96:97], v[76:77] op_sel_hi:[0,1,1]
	ds_read2_b32 v[96:97], v141 offset0:16 offset1:18
	ds_read2_b32 v[98:99], v141 offset0:144 offset1:146
	s_waitcnt lgkmcnt(1)
	v_mov_b32_e32 v100, v96
	s_waitcnt lgkmcnt(0)
	v_mov_b32_e32 v101, v98
	v_pk_fma_f32 v[78:79], v[0:1], v[100:101], v[78:79] op_sel_hi:[0,1,1]
	ds_read2_b32 v[100:101], v140 offset0:16 offset1:18
	ds_read2_b32 v[102:103], v140 offset0:144 offset1:146
	v_mov_b32_e32 v98, v97
	s_waitcnt lgkmcnt(1)
	v_mov_b32_e32 v104, v100
	s_waitcnt lgkmcnt(0)
	v_mov_b32_e32 v105, v102
	v_pk_fma_f32 v[80:81], v[0:1], v[104:105], v[80:81] op_sel_hi:[0,1,1]
	ds_read2_b32 v[104:105], v139 offset0:16 offset1:18
	ds_read2_b32 v[106:107], v139 offset0:144 offset1:146
	v_mov_b32_e32 v102, v101
	s_waitcnt lgkmcnt(1)
; __global__ void __launch_bounds__(512, 2) mk_fwd(Args args) {
;     ...
; #pragma unroll 16
;                 for (int i = 0; i < 64; ++i) { const float w = wp[(size_t)(2 * i) * 6144];
; #pragma unroll
;                     for (int b = 0; b < 17; ++b) acc[b] += sc[b * 128 + 2 * i + hi] * w; }
	v_mov_b32_e32 v108, v104
	s_waitcnt lgkmcnt(0)
	v_mov_b32_e32 v109, v106
	v_pk_fma_f32 v[82:83], v[0:1], v[108:109], v[82:83] op_sel_hi:[0,1,1]
	ds_read2_b32 v[108:109], v138 offset0:16 offset1:18
	ds_read2_b32 v[110:111], v138 offset0:144 offset1:146
	ds_read2_b32 v[114:115], v134 offset0:16 offset1:18
	ds_read2_b32 v[116:117], v134 offset0:144 offset1:146
	ds_read2_b32 v[120:121], v135 offset0:16 offset1:18
	ds_read2_b32 v[122:123], v135 offset0:144 offset1:146
	ds_read2_b32 v[126:127], v136 offset0:16 offset1:18
	ds_read2_b32 v[144:145], v136 offset0:144 offset1:146
	s_waitcnt lgkmcnt(7)
	v_mov_b32_e32 v112, v108
	s_waitcnt lgkmcnt(6)
	v_mov_b32_e32 v113, v110
	ds_read2_b32 v[148:149], v137 offset0:16 offset1:18
	v_pk_fma_f32 v[112:113], v[0:1], v[112:113], v[84:85] op_sel_hi:[0,1,1]
	s_waitcnt lgkmcnt(6)
	v_mov_b32_e32 v84, v114
	s_waitcnt lgkmcnt(5)
	v_mov_b32_e32 v85, v116
	v_pk_fma_f32 v[118:119], v[0:1], v[84:85], v[86:87] op_sel_hi:[0,1,1]
	s_waitcnt lgkmcnt(4)
	v_mov_b32_e32 v84, v120
	s_waitcnt lgkmcnt(3)
	v_mov_b32_e32 v85, v122
	v_pk_fma_f32 v[124:125], v[0:1], v[84:85], v[88:89] op_sel_hi:[0,1,1]
	s_waitcnt lgkmcnt(2)
	v_mov_b32_e32 v84, v126
	s_waitcnt lgkmcnt(1)
	v_mov_b32_e32 v85, v144
	v_pk_fma_f32 v[146:147], v[0:1], v[84:85], v[90:91] op_sel_hi:[0,1,1]
	v_lshl_add_u64 v[84:85], s[4:5], 2, v[74:75]
	s_waitcnt lgkmcnt(0)
	v_fmac_f32_e32 v133, v0, v148
	v_mov_b32_e32 v0, v193
	s_add_i32 s4, s46, 0x1e000
	v_mov_b32_e32 v106, v105
	v_mov_b32_e32 v110, v109
	v_mov_b32_e32 v116, v115
	v_mov_b32_e32 v122, v121
	v_mov_b32_e32 v144, v127
	v_lshl_add_u64 v[92:93], s[4:5], 2, v[74:75]
	s_add_i32 s4, s46, 0x21000
	v_lshl_add_u64 v[126:127], s[4:5], 2, v[74:75]
	s_add_i32 s4, s46, 0x24000
	v_pk_fma_f32 v[90:91], v[0:1], v[94:95], v[76:77] op_sel_hi:[0,1,1]
	v_pk_fma_f32 v[88:89], v[0:1], v[98:99], v[78:79] op_sel_hi:[0,1,1]
	v_pk_fma_f32 v[86:87], v[0:1], v[102:103], v[80:81] op_sel_hi:[0,1,1]
	v_pk_fma_f32 v[84:85], v[0:1], v[106:107], v[82:83] op_sel_hi:[0,1,1]
	v_pk_fma_f32 v[82:83], v[0:1], v[110:111], v[112:113] op_sel_hi:[0,1,1]
	v_pk_fma_f32 v[80:81], v[0:1], v[116:117], v[118:119] op_sel_hi:[0,1,1]
	v_pk_fma_f32 v[78:79], v[0:1], v[122:123], v[124:125] op_sel_hi:[0,1,1]
	v_pk_fma_f32 v[76:77], v[0:1], v[144:145], v[146:147] op_sel_hi:[0,1,1]
	v_fmac_f32_e32 v133, v0, v149
	v_mov_b32_e32 v0, v194
	ds_read2_b32 v[92:93], v142 offset0:20 offset1:22
	ds_read2_b32 v[94:95], v142 offset0:148 offset1:150
	s_waitcnt lgkmcnt(1)
	v_mov_b32_e32 v96, v92
	s_waitcnt lgkmcnt(0)
	v_mov_b32_e32 v97, v94
	v_mov_b32_e32 v94, v93
	v_lshl_add_u64 v[92:93], s[4:5], 2, v[74:75]
	s_add_i32 s4, s46, 0x27000
	v_pk_fma_f32 v[90:91], v[0:1], v[96:97], v[90:91] op_sel_hi:[0,1,1]
	ds_read2_b32 v[96:97], v141 offset0:20 offset1:22
	ds_read2_b32 v[98:99], v141 offset0:148 offset1:150
	s_waitcnt lgkmcnt(1)
	v_mov_b32_e32 v100, v96
	s_waitcnt lgkmcnt(0)
	v_mov_b32_e32 v101, v98
	v_pk_fma_f32 v[88:89], v[0:1], v[100:101], v[88:89] op_sel_hi:[0,1,1]
	ds_read2_b32 v[100:101], v140 offset0:20 offset1:22
	ds_read2_b32 v[102:103], v140 offset0:148 offset1:150
	v_mov_b32_e32 v98, v97
	s_waitcnt lgkmcnt(1)
	v_mov_b32_e32 v104, v100
	s_waitcnt lgkmcnt(0)
	v_mov_b32_e32 v105, v102
	v_pk_fma_f32 v[86:87], v[0:1], v[104:105], v[86:87] op_sel_hi:[0,1,1]
	ds_read2_b32 v[104:105], v139 offset0:20 offset1:22
	ds_read2_b32 v[106:107], v139 offset0:148 offset1:150
	v_mov_b32_e32 v102, v101
	s_waitcnt lgkmcnt(1)
	v_mov_b32_e32 v108, v104
	s_waitcnt lgkmcnt(0)
	v_mov_b32_e32 v109, v106
	v_pk_fma_f32 v[84:85], v[0:1], v[108:109], v[84:85] op_sel_hi:[0,1,1]
	ds_read2_b32 v[108:109], v138 offset0:20 offset1:22
	ds_read2_b32 v[110:111], v138 offset0:148 offset1:150
	v_mov_b32_e32 v106, v105
	s_waitcnt lgkmcnt(1)
	v_mov_b32_e32 v112, v108
	s_waitcnt lgkmcnt(0)
	v_mov_b32_e32 v113, v110
	v_pk_fma_f32 v[82:83], v[0:1], v[112:113], v[82:83] op_sel_hi:[0,1,1]
	ds_read2_b32 v[112:113], v134 offset0:20 offset1:22
	ds_read2_b32 v[114:115], v134 offset0:148 offset1:150
	v_mov_b32_e32 v110, v109
	s_waitcnt lgkmcnt(1)
	v_mov_b32_e32 v116, v112
	s_waitcnt lgkmcnt(0)
	v_mov_b32_e32 v117, v114
	v_pk_fma_f32 v[80:81], v[0:1], v[116:117], v[80:81] op_sel_hi:[0,1,1]
	ds_read2_b32 v[116:117], v135 offset0:20 offset1:22
	ds_read2_b32 v[118:119], v135 offset0:148 offset1:150
	v_mov_b32_e32 v114, v113
	s_waitcnt lgkmcnt(1)
	v_mov_b32_e32 v120, v116
	s_waitcnt lgkmcnt(0)
	v_mov_b32_e32 v121, v118
	v_pk_fma_f32 v[78:79], v[0:1], v[120:121], v[78:79] op_sel_hi:[0,1,1]
	ds_read2_b32 v[120:121], v136 offset0:20 offset1:22
	ds_read2_b32 v[122:123], v136 offset0:148 offset1:150
	v_mov_b32_e32 v118, v117
	s_waitcnt lgkmcnt(1)
	v_mov_b32_e32 v124, v120
	s_waitcnt lgkmcnt(0)
	v_mov_b32_e32 v125, v122
	v_pk_fma_f32 v[76:77], v[0:1], v[124:125], v[76:77] op_sel_hi:[0,1,1]
	ds_read2_b32 v[124:125], v137 offset0:20 offset1:22
	v_mov_b32_e32 v122, v121
	s_waitcnt lgkmcnt(0)
	v_fmac_f32_e32 v133, v0, v124
	v_mov_b32_e32 v0, v195
	v_pk_fma_f32 v[90:91], v[0:1], v[94:95], v[90:91] op_sel_hi:[0,1,1]
	v_pk_fma_f32 v[88:89], v[0:1], v[98:99], v[88:89] op_sel_hi:[0,1,1]
	v_pk_fma_f32 v[86:87], v[0:1], v[102:103], v[86:87] op_sel_hi:[0,1,1]
	v_pk_fma_f32 v[84:85], v[0:1], v[106:107], v[84:85] op_sel_hi:[0,1,1]
	v_pk_fma_f32 v[82:83], v[0:1], v[110:111], v[82:83] op_sel_hi:[0,1,1]
	v_pk_fma_f32 v[80:81], v[0:1], v[114:115], v[80:81] op_sel_hi:[0,1,1]
	v_pk_fma_f32 v[78:79], v[0:1], v[118:119], v[78:79] op_sel_hi:[0,1,1]
	v_pk_fma_f32 v[76:77], v[0:1], v[122:123], v[76:77] op_sel_hi:[0,1,1]
	v_fmac_f32_e32 v133, v0, v125
	v_mov_b32_e32 v0, v196
	ds_read2_b32 v[92:93], v142 offset0:24 offset1:26
	ds_read2_b32 v[94:95], v142 offset0:152 offset1:154
	s_waitcnt lgkmcnt(1)
; #define LAS __attribute__((address_space(3)))
; __global__ void __launch_bounds__(512, 2) mk_fwd(Args args) {
;     ...
; #pragma unroll 16
;                 for (int i = 0; i < 64; ++i) { const float w = wp[(size_t)(2 * i) * 6144];
; #pragma unroll
;                     for (int b = 0; b < 17; ++b) acc[b] += sc[b * 128 + 2 * i + hi] * w; }
;                 LAS float* red = (LAS float*)(lds + 81920);
; #pragma unroll
;                 for (int b = 0; b < 17; ++b) { const float t = acc[b] + __shfl_xor(acc[b], 32); if (hi == 0) red[(wid * 17 + b) * 32 + cc] = t; }
	v_mov_b32_e32 v96, v92
	s_waitcnt lgkmcnt(0)
	v_mov_b32_e32 v97, v94
	v_mov_b32_e32 v94, v93
	v_pk_fma_f32 v[90:91], v[0:1], v[96:97], v[90:91] op_sel_hi:[0,1,1]
	ds_read2_b32 v[96:97], v141 offset0:24 offset1:26
	ds_read2_b32 v[98:99], v141 offset0:152 offset1:154
	s_waitcnt lgkmcnt(1)
	v_mov_b32_e32 v100, v96
	s_waitcnt lgkmcnt(0)
	v_mov_b32_e32 v101, v98
	v_pk_fma_f32 v[88:89], v[0:1], v[100:101], v[88:89] op_sel_hi:[0,1,1]
	ds_read2_b32 v[100:101], v140 offset0:24 offset1:26
	ds_read2_b32 v[102:103], v140 offset0:152 offset1:154
	v_mov_b32_e32 v98, v97
	s_waitcnt lgkmcnt(1)
	v_mov_b32_e32 v104, v100
	s_waitcnt lgkmcnt(0)
	v_mov_b32_e32 v105, v102
	v_pk_fma_f32 v[86:87], v[0:1], v[104:105], v[86:87] op_sel_hi:[0,1,1]
	ds_read2_b32 v[104:105], v139 offset0:24 offset1:26
	ds_read2_b32 v[106:107], v139 offset0:152 offset1:154
	v_mov_b32_e32 v102, v101
	s_waitcnt lgkmcnt(1)
	v_mov_b32_e32 v108, v104
	s_waitcnt lgkmcnt(0)
	v_mov_b32_e32 v109, v106
	v_pk_fma_f32 v[84:85], v[0:1], v[108:109], v[84:85] op_sel_hi:[0,1,1]
	ds_read2_b32 v[108:109], v138 offset0:24 offset1:26
	ds_read2_b32 v[110:111], v138 offset0:152 offset1:154
	v_mov_b32_e32 v106, v105
	s_waitcnt lgkmcnt(1)
	v_mov_b32_e32 v112, v108
	s_waitcnt lgkmcnt(0)
	v_mov_b32_e32 v113, v110
	v_pk_fma_f32 v[82:83], v[0:1], v[112:113], v[82:83] op_sel_hi:[0,1,1]
	ds_read2_b32 v[112:113], v134 offset0:24 offset1:26
	ds_read2_b32 v[114:115], v134 offset0:152 offset1:154
	v_mov_b32_e32 v110, v109
	s_waitcnt lgkmcnt(1)
	v_mov_b32_e32 v116, v112
	s_waitcnt lgkmcnt(0)
	v_mov_b32_e32 v117, v114
	v_pk_fma_f32 v[80:81], v[0:1], v[116:117], v[80:81] op_sel_hi:[0,1,1]
	ds_read2_b32 v[116:117], v135 offset0:24 offset1:26
	ds_read2_b32 v[118:119], v135 offset0:152 offset1:154
	ds_read2_b32 v[122:123], v136 offset0:24 offset1:26
	ds_read2_b32 v[124:125], v136 offset0:152 offset1:154
	ds_read2_b32 v[144:145], v137 offset0:24 offset1:26
	v_mov_b32_e32 v114, v113
	s_waitcnt lgkmcnt(4)
	v_mov_b32_e32 v120, v116
	s_waitcnt lgkmcnt(3)
	v_mov_b32_e32 v121, v118
	v_pk_fma_f32 v[120:121], v[0:1], v[120:121], v[78:79] op_sel_hi:[0,1,1]
	s_waitcnt lgkmcnt(2)
	v_mov_b32_e32 v78, v122
	s_waitcnt lgkmcnt(1)
	v_mov_b32_e32 v79, v124
	v_pk_fma_f32 v[126:127], v[0:1], v[78:79], v[76:77] op_sel_hi:[0,1,1]
	v_lshl_add_u64 v[76:77], s[4:5], 2, v[74:75]
	s_waitcnt lgkmcnt(0)
	v_fmac_f32_e32 v133, v0, v144
	v_mov_b32_e32 v0, v197
	s_add_i32 s4, s46, 0x2a000
	v_mov_b32_e32 v118, v117
	v_mov_b32_e32 v124, v123
	v_lshl_add_u64 v[92:93], s[4:5], 2, v[74:75]
	s_add_i32 s46, s46, 0x2d000
	s_cmp_eq_u32 s7, 64
	v_pk_fma_f32 v[90:91], v[0:1], v[94:95], v[90:91] op_sel_hi:[0,1,1]
	v_pk_fma_f32 v[88:89], v[0:1], v[98:99], v[88:89] op_sel_hi:[0,1,1]
	v_pk_fma_f32 v[86:87], v[0:1], v[102:103], v[86:87] op_sel_hi:[0,1,1]
	v_pk_fma_f32 v[84:85], v[0:1], v[106:107], v[84:85] op_sel_hi:[0,1,1]
	v_pk_fma_f32 v[82:83], v[0:1], v[110:111], v[82:83] op_sel_hi:[0,1,1]
	v_pk_fma_f32 v[78:79], v[0:1], v[114:115], v[80:81] op_sel_hi:[0,1,1]
	v_pk_fma_f32 v[76:77], v[0:1], v[118:119], v[120:121] op_sel_hi:[0,1,1]
	v_pk_fma_f32 v[80:81], v[0:1], v[124:125], v[126:127] op_sel_hi:[0,1,1]
	v_fmac_f32_e32 v133, v0, v145
	v_mov_b32_e32 v0, v198
	ds_read2_b32 v[120:121], v142 offset0:28 offset1:30
	ds_read2_b32 v[122:123], v142 offset0:156 offset1:158
	ds_read2_b32 v[106:107], v141 offset0:28 offset1:30
	ds_read2_b32 v[112:113], v141 offset0:156 offset1:158
	ds_read2_b32 v[108:109], v140 offset0:28 offset1:30
	ds_read2_b32 v[104:105], v140 offset0:156 offset1:158
	ds_read2_b32 v[98:99], v139 offset0:28 offset1:30
	ds_read2_b32 v[102:103], v139 offset0:156 offset1:158
	ds_read2_b32 v[100:101], v138 offset0:28 offset1:30
	ds_read2_b32 v[96:97], v138 offset0:156 offset1:158
	s_waitcnt lgkmcnt(9)
	v_mov_b32_e32 v92, v120
	s_waitcnt lgkmcnt(8)
	v_mov_b32_e32 v93, v122
	v_lshl_add_u64 v[126:127], s[46:47], 2, v[74:75]
	v_mov_b32_e32 v122, v121
	v_pk_fma_f32 v[124:125], v[0:1], v[92:93], v[90:91] op_sel_hi:[0,1,1]
	s_waitcnt lgkmcnt(7)
	v_mov_b32_e32 v90, v106
	s_waitcnt lgkmcnt(6)
	v_mov_b32_e32 v91, v112
	v_pk_fma_f32 v[118:119], v[0:1], v[90:91], v[88:89] op_sel_hi:[0,1,1]
	s_waitcnt lgkmcnt(5)
	v_mov_b32_e32 v88, v108
	s_waitcnt lgkmcnt(4)
	v_mov_b32_e32 v89, v104
	v_pk_fma_f32 v[114:115], v[0:1], v[88:89], v[86:87] op_sel_hi:[0,1,1]
	s_waitcnt lgkmcnt(3)
	v_mov_b32_e32 v86, v98
	s_waitcnt lgkmcnt(2)
	v_mov_b32_e32 v87, v102
	v_pk_fma_f32 v[116:117], v[0:1], v[86:87], v[84:85] op_sel_hi:[0,1,1]
	s_waitcnt lgkmcnt(1)
	v_mov_b32_e32 v84, v100
	s_waitcnt lgkmcnt(0)
	v_mov_b32_e32 v85, v96
	ds_read2_b32 v[92:93], v134 offset0:28 offset1:30
	ds_read2_b32 v[90:91], v134 offset0:156 offset1:158
	v_pk_fma_f32 v[110:111], v[0:1], v[84:85], v[82:83] op_sel_hi:[0,1,1]
	ds_read2_b32 v[86:87], v135 offset0:28 offset1:30
	ds_read2_b32 v[84:85], v135 offset0:156 offset1:158
	v_mov_b32_e32 v112, v107
	s_waitcnt lgkmcnt(3)
	v_mov_b32_e32 v82, v92
	s_waitcnt lgkmcnt(2)
	v_mov_b32_e32 v83, v90
	v_pk_fma_f32 v[94:95], v[0:1], v[82:83], v[78:79] op_sel_hi:[0,1,1]
	s_waitcnt lgkmcnt(1)
	v_mov_b32_e32 v78, v86
	s_waitcnt lgkmcnt(0)
	v_mov_b32_e32 v79, v84
	v_pk_fma_f32 v[88:89], v[0:1], v[78:79], v[76:77] op_sel_hi:[0,1,1]
	ds_read2_b32 v[78:79], v136 offset0:28 offset1:30
	ds_read2_b32 v[76:77], v136 offset0:156 offset1:158
	v_mov_b32_e32 v104, v109
	v_mov_b32_e32 v102, v99
	v_mov_b32_e32 v96, v101
	s_waitcnt lgkmcnt(1)
	v_mov_b32_e32 v82, v78
	s_waitcnt lgkmcnt(0)
	v_mov_b32_e32 v83, v76
	v_pk_fma_f32 v[80:81], v[0:1], v[82:83], v[80:81] op_sel_hi:[0,1,1]
	ds_read2_b32 v[82:83], v137 offset0:28 offset1:30
	v_mov_b32_e32 v90, v93
	v_mov_b32_e32 v84, v87
	v_mov_b32_e32 v76, v79
	s_waitcnt lgkmcnt(0)
	v_fmac_f32_e32 v133, v0, v82
	v_mov_b32_e32 v0, v199
	v_pk_fma_f32 v[120:121], v[0:1], v[122:123], v[124:125] op_sel_hi:[0,1,1]
	v_pk_fma_f32 v[106:107], v[0:1], v[112:113], v[118:119] op_sel_hi:[0,1,1]
	v_pk_fma_f32 v[104:105], v[0:1], v[104:105], v[114:115] op_sel_hi:[0,1,1]
	v_pk_fma_f32 v[98:99], v[0:1], v[102:103], v[116:117] op_sel_hi:[0,1,1]
	v_pk_fma_f32 v[96:97], v[0:1], v[96:97], v[110:111] op_sel_hi:[0,1,1]
	v_pk_fma_f32 v[90:91], v[0:1], v[90:91], v[94:95] op_sel_hi:[0,1,1]
	v_pk_fma_f32 v[84:85], v[0:1], v[84:85], v[88:89] op_sel_hi:[0,1,1]
	v_pk_fma_f32 v[80:81], v[0:1], v[76:77], v[80:81] op_sel_hi:[0,1,1]
	v_fmac_f32_e32 v133, v0, v83
	s_cbranch_scc0 .LBB0_516
	ds_bpermute_b32 v74, v130, v120
	s_mul_i32 s4, s3, 0x880
	v_add_u32_e32 v0, s4, v132
	s_and_saveexec_b64 s[4:5], s[38:39]
	s_cbranch_execz .LBB0_519
	s_waitcnt lgkmcnt(0)
	v_add_f32_e32 v74, v120, v74
	ds_write_b32 v0, v74
